# prologue cond-GEMV with 32 weight rows in flight per wave; NA K-tile row stride 288 (conflict-free ds_read_b128)
# speedup vs baseline: 1.0113x; 1.0113x over previous
.LBB0_13:
	s_mul_hi_i32 s0, s18, 0x2aaaaaab
	s_lshr_b32 s1, s0, 31
	s_ashr_i32 s19, s0, 4
	s_add_i32 s19, s19, s1
	s_mov_b64 s[0:1], s[52:53]
	s_mul_i32 s20, s19, 0x1800
	v_lshl_add_u64 v[16:17], s[0:1], 0, v[14:15]
	s_sub_i32 s0, s10, s20
	s_ashr_i32 s1, s0, 31
	s_mul_i32 s7, s19, 0x3000000
	s_lshl_b64 s[0:1], s[0:1], 2
	s_mul_hi_i32 s6, s19, 0x3000000
	s_add_u32 s0, s7, s0
	s_addc_u32 s1, s6, s1
	v_lshl_add_u64 v[16:17], v[16:17], 0, s[0:1]
	s_mov_b64 s[6:7], 0
	v_mov_b32_e32 v7, v3
	v_mov_b32_e32 v5, 0
	v_mov_b32_e32 v18, 0
	v_mov_b32_e32 v19, v9
	v_mov_b32_e32 v20, 0
	v_mov_b32_e32 v21, v9
	v_readfirstlane_b32 s30, v16
	v_readfirstlane_b32 s31, v17
	v_mov_b32_e32 v76, v8
	v_add_u32_e32 v77, 0x6000, v8
	v_add_u32_e32 v78, 0xc000, v8
	v_add_u32_e32 v79, 0x12000, v8
	s_nop 1
	global_load_dword v22, v76, s[30:31] nt
	global_load_dword v23, v77, s[30:31] nt
	global_load_dword v24, v78, s[30:31] nt
	global_load_dword v25, v79, s[30:31] nt
	v_add_u32_e32 v76, 0x18000, v76
	v_add_u32_e32 v77, 0x18000, v77
	v_add_u32_e32 v78, 0x18000, v78
	v_add_u32_e32 v79, 0x18000, v79
	global_load_dword v26, v76, s[30:31] nt
	global_load_dword v27, v77, s[30:31] nt
	global_load_dword v28, v78, s[30:31] nt
	global_load_dword v29, v79, s[30:31] nt
	v_add_u32_e32 v76, 0x18000, v76
	v_add_u32_e32 v77, 0x18000, v77
	v_add_u32_e32 v78, 0x18000, v78
	v_add_u32_e32 v79, 0x18000, v79
	global_load_dword v30, v76, s[30:31] nt
	global_load_dword v31, v77, s[30:31] nt
	global_load_dword v32, v78, s[30:31] nt
	global_load_dword v33, v79, s[30:31] nt
	v_add_u32_e32 v76, 0x18000, v76
	v_add_u32_e32 v77, 0x18000, v77
	v_add_u32_e32 v78, 0x18000, v78
	v_add_u32_e32 v79, 0x18000, v79
	global_load_dword v36, v76, s[30:31] nt
	global_load_dword v37, v77, s[30:31] nt
	global_load_dword v38, v78, s[30:31] nt
	global_load_dword v39, v79, s[30:31] nt
	v_add_u32_e32 v76, 0x18000, v76
	v_add_u32_e32 v77, 0x18000, v77
	v_add_u32_e32 v78, 0x18000, v78
	v_add_u32_e32 v79, 0x18000, v79
	global_load_dword v40, v76, s[30:31] nt
	global_load_dword v41, v77, s[30:31] nt
	global_load_dword v42, v78, s[30:31] nt
	global_load_dword v43, v79, s[30:31] nt
	v_add_u32_e32 v76, 0x18000, v76
	v_add_u32_e32 v77, 0x18000, v77
	v_add_u32_e32 v78, 0x18000, v78
	v_add_u32_e32 v79, 0x18000, v79
	global_load_dword v44, v76, s[30:31] nt
	global_load_dword v45, v77, s[30:31] nt
	global_load_dword v46, v78, s[30:31] nt
	global_load_dword v47, v79, s[30:31] nt
	v_add_u32_e32 v76, 0x18000, v76
	v_add_u32_e32 v77, 0x18000, v77
	v_add_u32_e32 v78, 0x18000, v78
	v_add_u32_e32 v79, 0x18000, v79
	global_load_dword v48, v76, s[30:31] nt
	global_load_dword v49, v77, s[30:31] nt
	global_load_dword v50, v78, s[30:31] nt
	global_load_dword v51, v79, s[30:31] nt
	v_add_u32_e32 v76, 0x18000, v76
	v_add_u32_e32 v77, 0x18000, v77
	v_add_u32_e32 v78, 0x18000, v78
	v_add_u32_e32 v79, 0x18000, v79
	global_load_dword v52, v76, s[30:31] nt
	global_load_dword v53, v77, s[30:31] nt
	global_load_dword v54, v78, s[30:31] nt
	global_load_dword v55, v79, s[30:31] nt
	v_add_u32_e32 v76, 0x18000, v76
	v_add_u32_e32 v77, 0x18000, v77
	v_add_u32_e32 v78, 0x18000, v78
	v_add_u32_e32 v79, 0x18000, v79
	s_mov_b32 s6, 0
.Lmv_loop:
	s_waitcnt vmcnt(28)
	ds_read_b128 v[56:59], v7
	ds_read_b128 v[60:63], v7 offset:8192
	ds_read_b128 v[64:67], v7 offset:16384
	ds_read_b128 v[68:71], v7 offset:24576
	ds_read_b128 v[72:75], v7 offset:32768
	s_waitcnt lgkmcnt(0)
	v_fmac_f32_e32 v18, v56, v22
	v_fmac_f32_e32 v19, v60, v22
	v_fmac_f32_e32 v20, v64, v22
	v_fmac_f32_e32 v21, v68, v22
	v_fmac_f32_e32 v5, v72, v22
	v_fmac_f32_e32 v18, v57, v23
	v_fmac_f32_e32 v19, v61, v23
	v_fmac_f32_e32 v20, v65, v23
	v_fmac_f32_e32 v21, v69, v23
	v_fmac_f32_e32 v5, v73, v23
	v_fmac_f32_e32 v18, v58, v24
	v_fmac_f32_e32 v19, v62, v24
	v_fmac_f32_e32 v20, v66, v24
	v_fmac_f32_e32 v21, v70, v24
	v_fmac_f32_e32 v5, v74, v24
	v_fmac_f32_e32 v18, v59, v25
	v_fmac_f32_e32 v19, v63, v25
	v_fmac_f32_e32 v20, v67, v25
	v_fmac_f32_e32 v21, v71, v25
	v_fmac_f32_e32 v5, v75, v25
	v_add_u32_e32 v7, 16, v7
	global_load_dword v22, v76, s[30:31] nt
	global_load_dword v23, v77, s[30:31] nt
	global_load_dword v24, v78, s[30:31] nt
	global_load_dword v25, v79, s[30:31] nt
	v_add_u32_e32 v76, 0x18000, v76
	v_add_u32_e32 v77, 0x18000, v77
	v_add_u32_e32 v78, 0x18000, v78
	v_add_u32_e32 v79, 0x18000, v79
	s_waitcnt vmcnt(28)
	ds_read_b128 v[56:59], v7
	ds_read_b128 v[60:63], v7 offset:8192
	ds_read_b128 v[64:67], v7 offset:16384
	ds_read_b128 v[68:71], v7 offset:24576
	ds_read_b128 v[72:75], v7 offset:32768
	s_waitcnt lgkmcnt(0)
	v_fmac_f32_e32 v18, v56, v26
	v_fmac_f32_e32 v19, v60, v26
	v_fmac_f32_e32 v20, v64, v26
	v_fmac_f32_e32 v21, v68, v26
	v_fmac_f32_e32 v5, v72, v26
	v_fmac_f32_e32 v18, v57, v27
	v_fmac_f32_e32 v19, v61, v27
	v_fmac_f32_e32 v20, v65, v27
	v_fmac_f32_e32 v21, v69, v27
	v_fmac_f32_e32 v5, v73, v27
	v_fmac_f32_e32 v18, v58, v28
	v_fmac_f32_e32 v19, v62, v28
	v_fmac_f32_e32 v20, v66, v28
	v_fmac_f32_e32 v21, v70, v28
	v_fmac_f32_e32 v5, v74, v28
	v_fmac_f32_e32 v18, v59, v29
	v_fmac_f32_e32 v19, v63, v29
	v_fmac_f32_e32 v20, v67, v29
	v_fmac_f32_e32 v21, v71, v29
	v_fmac_f32_e32 v5, v75, v29
	v_add_u32_e32 v7, 16, v7
	global_load_dword v26, v76, s[30:31] nt
	global_load_dword v27, v77, s[30:31] nt
	global_load_dword v28, v78, s[30:31] nt
	global_load_dword v29, v79, s[30:31] nt
	v_add_u32_e32 v76, 0x18000, v76
	v_add_u32_e32 v77, 0x18000, v77
	v_add_u32_e32 v78, 0x18000, v78
	v_add_u32_e32 v79, 0x18000, v79
	s_waitcnt vmcnt(28)
	ds_read_b128 v[56:59], v7
	ds_read_b128 v[60:63], v7 offset:8192
	ds_read_b128 v[64:67], v7 offset:16384
	ds_read_b128 v[68:71], v7 offset:24576
	ds_read_b128 v[72:75], v7 offset:32768
	s_waitcnt lgkmcnt(0)
	v_fmac_f32_e32 v18, v56, v30
	v_fmac_f32_e32 v19, v60, v30
	v_fmac_f32_e32 v20, v64, v30
	v_fmac_f32_e32 v21, v68, v30
	v_fmac_f32_e32 v5, v72, v30
	v_fmac_f32_e32 v18, v57, v31
	v_fmac_f32_e32 v19, v61, v31
	v_fmac_f32_e32 v20, v65, v31
	v_fmac_f32_e32 v21, v69, v31
	v_fmac_f32_e32 v5, v73, v31
	v_fmac_f32_e32 v18, v58, v32
	v_fmac_f32_e32 v19, v62, v32
	v_fmac_f32_e32 v20, v66, v32
	v_fmac_f32_e32 v21, v70, v32
	v_fmac_f32_e32 v5, v74, v32
	v_fmac_f32_e32 v18, v59, v33
	v_fmac_f32_e32 v19, v63, v33
	v_fmac_f32_e32 v20, v67, v33
	v_fmac_f32_e32 v21, v71, v33
	v_fmac_f32_e32 v5, v75, v33
	v_add_u32_e32 v7, 16, v7
	global_load_dword v30, v76, s[30:31] nt
	global_load_dword v31, v77, s[30:31] nt
	global_load_dword v32, v78, s[30:31] nt
	global_load_dword v33, v79, s[30:31] nt
	v_add_u32_e32 v76, 0x18000, v76
	v_add_u32_e32 v77, 0x18000, v77
	v_add_u32_e32 v78, 0x18000, v78
	v_add_u32_e32 v79, 0x18000, v79
	s_waitcnt vmcnt(28)
	ds_read_b128 v[56:59], v7
	ds_read_b128 v[60:63], v7 offset:8192
	ds_read_b128 v[64:67], v7 offset:16384
	ds_read_b128 v[68:71], v7 offset:24576
	ds_read_b128 v[72:75], v7 offset:32768
	s_waitcnt lgkmcnt(0)
	v_fmac_f32_e32 v18, v56, v36
	v_fmac_f32_e32 v19, v60, v36
	v_fmac_f32_e32 v20, v64, v36
	v_fmac_f32_e32 v21, v68, v36
	v_fmac_f32_e32 v5, v72, v36
	v_fmac_f32_e32 v18, v57, v37
	v_fmac_f32_e32 v19, v61, v37
	v_fmac_f32_e32 v20, v65, v37
	v_fmac_f32_e32 v21, v69, v37
	v_fmac_f32_e32 v5, v73, v37
	v_fmac_f32_e32 v18, v58, v38
	v_fmac_f32_e32 v19, v62, v38
	v_fmac_f32_e32 v20, v66, v38
	v_fmac_f32_e32 v21, v70, v38
	v_fmac_f32_e32 v5, v74, v38
	v_fmac_f32_e32 v18, v59, v39
	v_fmac_f32_e32 v19, v63, v39
	v_fmac_f32_e32 v20, v67, v39
	v_fmac_f32_e32 v21, v71, v39
	v_fmac_f32_e32 v5, v75, v39
	v_add_u32_e32 v7, 16, v7
	global_load_dword v36, v76, s[30:31] nt
	global_load_dword v37, v77, s[30:31] nt
	global_load_dword v38, v78, s[30:31] nt
	global_load_dword v39, v79, s[30:31] nt
	v_add_u32_e32 v76, 0x18000, v76
	v_add_u32_e32 v77, 0x18000, v77
	v_add_u32_e32 v78, 0x18000, v78
	v_add_u32_e32 v79, 0x18000, v79
	s_waitcnt vmcnt(28)
	ds_read_b128 v[56:59], v7
	ds_read_b128 v[60:63], v7 offset:8192
	ds_read_b128 v[64:67], v7 offset:16384
	ds_read_b128 v[68:71], v7 offset:24576
	ds_read_b128 v[72:75], v7 offset:32768
	s_waitcnt lgkmcnt(0)
	v_fmac_f32_e32 v18, v56, v40
	v_fmac_f32_e32 v19, v60, v40
	v_fmac_f32_e32 v20, v64, v40
	v_fmac_f32_e32 v21, v68, v40
	v_fmac_f32_e32 v5, v72, v40
	v_fmac_f32_e32 v18, v57, v41
	v_fmac_f32_e32 v19, v61, v41
	v_fmac_f32_e32 v20, v65, v41
	v_fmac_f32_e32 v21, v69, v41
	v_fmac_f32_e32 v5, v73, v41
	v_fmac_f32_e32 v18, v58, v42
	v_fmac_f32_e32 v19, v62, v42
	v_fmac_f32_e32 v20, v66, v42
	v_fmac_f32_e32 v21, v70, v42
	v_fmac_f32_e32 v5, v74, v42
	v_fmac_f32_e32 v18, v59, v43
	v_fmac_f32_e32 v19, v63, v43
	v_fmac_f32_e32 v20, v67, v43
	v_fmac_f32_e32 v21, v71, v43
	v_fmac_f32_e32 v5, v75, v43
	v_add_u32_e32 v7, 16, v7
	global_load_dword v40, v76, s[30:31] nt
	global_load_dword v41, v77, s[30:31] nt
	global_load_dword v42, v78, s[30:31] nt
	global_load_dword v43, v79, s[30:31] nt
	v_add_u32_e32 v76, 0x18000, v76
	v_add_u32_e32 v77, 0x18000, v77
	v_add_u32_e32 v78, 0x18000, v78
	v_add_u32_e32 v79, 0x18000, v79
	s_waitcnt vmcnt(28)
	ds_read_b128 v[56:59], v7
	ds_read_b128 v[60:63], v7 offset:8192
	ds_read_b128 v[64:67], v7 offset:16384
	ds_read_b128 v[68:71], v7 offset:24576
	ds_read_b128 v[72:75], v7 offset:32768
	s_waitcnt lgkmcnt(0)
	v_fmac_f32_e32 v18, v56, v44
	v_fmac_f32_e32 v19, v60, v44
	v_fmac_f32_e32 v20, v64, v44
	v_fmac_f32_e32 v21, v68, v44
	v_fmac_f32_e32 v5, v72, v44
	v_fmac_f32_e32 v18, v57, v45
	v_fmac_f32_e32 v19, v61, v45
	v_fmac_f32_e32 v20, v65, v45
	v_fmac_f32_e32 v21, v69, v45
	v_fmac_f32_e32 v5, v73, v45
	v_fmac_f32_e32 v18, v58, v46
	v_fmac_f32_e32 v19, v62, v46
	v_fmac_f32_e32 v20, v66, v46
	v_fmac_f32_e32 v21, v70, v46
	v_fmac_f32_e32 v5, v74, v46
	v_fmac_f32_e32 v18, v59, v47
	v_fmac_f32_e32 v19, v63, v47
	v_fmac_f32_e32 v20, v67, v47
	v_fmac_f32_e32 v21, v71, v47
	v_fmac_f32_e32 v5, v75, v47
	v_add_u32_e32 v7, 16, v7
	global_load_dword v44, v76, s[30:31] nt
	global_load_dword v45, v77, s[30:31] nt
	global_load_dword v46, v78, s[30:31] nt
	global_load_dword v47, v79, s[30:31] nt
	v_add_u32_e32 v76, 0x18000, v76
	v_add_u32_e32 v77, 0x18000, v77
	v_add_u32_e32 v78, 0x18000, v78
	v_add_u32_e32 v79, 0x18000, v79
	s_waitcnt vmcnt(28)
	ds_read_b128 v[56:59], v7
	ds_read_b128 v[60:63], v7 offset:8192
	ds_read_b128 v[64:67], v7 offset:16384
	ds_read_b128 v[68:71], v7 offset:24576
	ds_read_b128 v[72:75], v7 offset:32768
	s_waitcnt lgkmcnt(0)
	v_fmac_f32_e32 v18, v56, v48
	v_fmac_f32_e32 v19, v60, v48
	v_fmac_f32_e32 v20, v64, v48
	v_fmac_f32_e32 v21, v68, v48
	v_fmac_f32_e32 v5, v72, v48
	v_fmac_f32_e32 v18, v57, v49
	v_fmac_f32_e32 v19, v61, v49
	v_fmac_f32_e32 v20, v65, v49
	v_fmac_f32_e32 v21, v69, v49
	v_fmac_f32_e32 v5, v73, v49
	v_fmac_f32_e32 v18, v58, v50
	v_fmac_f32_e32 v19, v62, v50
	v_fmac_f32_e32 v20, v66, v50
	v_fmac_f32_e32 v21, v70, v50
	v_fmac_f32_e32 v5, v74, v50
	v_fmac_f32_e32 v18, v59, v51
	v_fmac_f32_e32 v19, v63, v51
	v_fmac_f32_e32 v20, v67, v51
	v_fmac_f32_e32 v21, v71, v51
	v_fmac_f32_e32 v5, v75, v51
	v_add_u32_e32 v7, 16, v7
	global_load_dword v48, v76, s[30:31] nt
	global_load_dword v49, v77, s[30:31] nt
	global_load_dword v50, v78, s[30:31] nt
	global_load_dword v51, v79, s[30:31] nt
	v_add_u32_e32 v76, 0x18000, v76
	v_add_u32_e32 v77, 0x18000, v77
	v_add_u32_e32 v78, 0x18000, v78
	v_add_u32_e32 v79, 0x18000, v79
	s_waitcnt vmcnt(28)
	ds_read_b128 v[56:59], v7
	ds_read_b128 v[60:63], v7 offset:8192
	ds_read_b128 v[64:67], v7 offset:16384
	ds_read_b128 v[68:71], v7 offset:24576
	ds_read_b128 v[72:75], v7 offset:32768
	s_waitcnt lgkmcnt(0)
	v_fmac_f32_e32 v18, v56, v52
	v_fmac_f32_e32 v19, v60, v52
	v_fmac_f32_e32 v20, v64, v52
	v_fmac_f32_e32 v21, v68, v52
	v_fmac_f32_e32 v5, v72, v52
	v_fmac_f32_e32 v18, v57, v53
	v_fmac_f32_e32 v19, v61, v53
	v_fmac_f32_e32 v20, v65, v53
	v_fmac_f32_e32 v21, v69, v53
	v_fmac_f32_e32 v5, v73, v53
	v_fmac_f32_e32 v18, v58, v54
	v_fmac_f32_e32 v19, v62, v54
	v_fmac_f32_e32 v20, v66, v54
	v_fmac_f32_e32 v21, v70, v54
	v_fmac_f32_e32 v5, v74, v54
	v_fmac_f32_e32 v18, v59, v55
	v_fmac_f32_e32 v19, v63, v55
	v_fmac_f32_e32 v20, v67, v55
	v_fmac_f32_e32 v21, v71, v55
	v_fmac_f32_e32 v5, v75, v55
	v_add_u32_e32 v7, 16, v7
	global_load_dword v52, v76, s[30:31] nt
	global_load_dword v53, v77, s[30:31] nt
	global_load_dword v54, v78, s[30:31] nt
	global_load_dword v55, v79, s[30:31] nt
	v_add_u32_e32 v76, 0x18000, v76
	v_add_u32_e32 v77, 0x18000, v77
	v_add_u32_e32 v78, 0x18000, v78
	v_add_u32_e32 v79, 0x18000, v79
	s_add_u32 s6, s6, 1
	s_cmp_lt_u32 s6, 7
	s_cbranch_scc1 .Lmv_loop
	s_waitcnt vmcnt(28)
	ds_read_b128 v[56:59], v7
	ds_read_b128 v[60:63], v7 offset:8192
	ds_read_b128 v[64:67], v7 offset:16384
	ds_read_b128 v[68:71], v7 offset:24576
	ds_read_b128 v[72:75], v7 offset:32768
	s_waitcnt lgkmcnt(0)
	v_fmac_f32_e32 v18, v56, v22
	v_fmac_f32_e32 v19, v60, v22
	v_fmac_f32_e32 v20, v64, v22
	v_fmac_f32_e32 v21, v68, v22
	v_fmac_f32_e32 v5, v72, v22
	v_fmac_f32_e32 v18, v57, v23
	v_fmac_f32_e32 v19, v61, v23
	v_fmac_f32_e32 v20, v65, v23
	v_fmac_f32_e32 v21, v69, v23
	v_fmac_f32_e32 v5, v73, v23
	v_fmac_f32_e32 v18, v58, v24
	v_fmac_f32_e32 v19, v62, v24
	v_fmac_f32_e32 v20, v66, v24
	v_fmac_f32_e32 v21, v70, v24
	v_fmac_f32_e32 v5, v74, v24
	v_fmac_f32_e32 v18, v59, v25
	v_fmac_f32_e32 v19, v63, v25
	v_fmac_f32_e32 v20, v67, v25
	v_fmac_f32_e32 v21, v71, v25
	v_fmac_f32_e32 v5, v75, v25
	v_add_u32_e32 v7, 16, v7
	s_waitcnt vmcnt(24)
	ds_read_b128 v[56:59], v7
	ds_read_b128 v[60:63], v7 offset:8192
	ds_read_b128 v[64:67], v7 offset:16384
	ds_read_b128 v[68:71], v7 offset:24576
	ds_read_b128 v[72:75], v7 offset:32768
	s_waitcnt lgkmcnt(0)
	v_fmac_f32_e32 v18, v56, v26
	v_fmac_f32_e32 v19, v60, v26
	v_fmac_f32_e32 v20, v64, v26
	v_fmac_f32_e32 v21, v68, v26
	v_fmac_f32_e32 v5, v72, v26
	v_fmac_f32_e32 v18, v57, v27
	v_fmac_f32_e32 v19, v61, v27
	v_fmac_f32_e32 v20, v65, v27
	v_fmac_f32_e32 v21, v69, v27
	v_fmac_f32_e32 v5, v73, v27
	v_fmac_f32_e32 v18, v58, v28
	v_fmac_f32_e32 v19, v62, v28
	v_fmac_f32_e32 v20, v66, v28
	v_fmac_f32_e32 v21, v70, v28
	v_fmac_f32_e32 v5, v74, v28
	v_fmac_f32_e32 v18, v59, v29
	v_fmac_f32_e32 v19, v63, v29
	v_fmac_f32_e32 v20, v67, v29
	v_fmac_f32_e32 v21, v71, v29
	v_fmac_f32_e32 v5, v75, v29
	v_add_u32_e32 v7, 16, v7
	s_waitcnt vmcnt(20)
	ds_read_b128 v[56:59], v7
	ds_read_b128 v[60:63], v7 offset:8192
	ds_read_b128 v[64:67], v7 offset:16384
	ds_read_b128 v[68:71], v7 offset:24576
	ds_read_b128 v[72:75], v7 offset:32768
	s_waitcnt lgkmcnt(0)
	v_fmac_f32_e32 v18, v56, v30
	v_fmac_f32_e32 v19, v60, v30
	v_fmac_f32_e32 v20, v64, v30
	v_fmac_f32_e32 v21, v68, v30
	v_fmac_f32_e32 v5, v72, v30
	v_fmac_f32_e32 v18, v57, v31
	v_fmac_f32_e32 v19, v61, v31
	v_fmac_f32_e32 v20, v65, v31
	v_fmac_f32_e32 v21, v69, v31
	v_fmac_f32_e32 v5, v73, v31
	v_fmac_f32_e32 v18, v58, v32
	v_fmac_f32_e32 v19, v62, v32
	v_fmac_f32_e32 v20, v66, v32
	v_fmac_f32_e32 v21, v70, v32
	v_fmac_f32_e32 v5, v74, v32
	v_fmac_f32_e32 v18, v59, v33
	v_fmac_f32_e32 v19, v63, v33
	v_fmac_f32_e32 v20, v67, v33
	v_fmac_f32_e32 v21, v71, v33
	v_fmac_f32_e32 v5, v75, v33
	v_add_u32_e32 v7, 16, v7
	s_waitcnt vmcnt(16)
	ds_read_b128 v[56:59], v7
	ds_read_b128 v[60:63], v7 offset:8192
	ds_read_b128 v[64:67], v7 offset:16384
	ds_read_b128 v[68:71], v7 offset:24576
	ds_read_b128 v[72:75], v7 offset:32768
	s_waitcnt lgkmcnt(0)
	v_fmac_f32_e32 v18, v56, v36
	v_fmac_f32_e32 v19, v60, v36
	v_fmac_f32_e32 v20, v64, v36
	v_fmac_f32_e32 v21, v68, v36
	v_fmac_f32_e32 v5, v72, v36
	v_fmac_f32_e32 v18, v57, v37
	v_fmac_f32_e32 v19, v61, v37
	v_fmac_f32_e32 v20, v65, v37
	v_fmac_f32_e32 v21, v69, v37
	v_fmac_f32_e32 v5, v73, v37
	v_fmac_f32_e32 v18, v58, v38
	v_fmac_f32_e32 v19, v62, v38
	v_fmac_f32_e32 v20, v66, v38
	v_fmac_f32_e32 v21, v70, v38
	v_fmac_f32_e32 v5, v74, v38
	v_fmac_f32_e32 v18, v59, v39
	v_fmac_f32_e32 v19, v63, v39
	v_fmac_f32_e32 v20, v67, v39
	v_fmac_f32_e32 v21, v71, v39
	v_fmac_f32_e32 v5, v75, v39
	v_add_u32_e32 v7, 16, v7
	s_waitcnt vmcnt(12)
	ds_read_b128 v[56:59], v7
	ds_read_b128 v[60:63], v7 offset:8192
	ds_read_b128 v[64:67], v7 offset:16384
	ds_read_b128 v[68:71], v7 offset:24576
	ds_read_b128 v[72:75], v7 offset:32768
	s_waitcnt lgkmcnt(0)
	v_fmac_f32_e32 v18, v56, v40
	v_fmac_f32_e32 v19, v60, v40
	v_fmac_f32_e32 v20, v64, v40
	v_fmac_f32_e32 v21, v68, v40
	v_fmac_f32_e32 v5, v72, v40
	v_fmac_f32_e32 v18, v57, v41
	v_fmac_f32_e32 v19, v61, v41
	v_fmac_f32_e32 v20, v65, v41
	v_fmac_f32_e32 v21, v69, v41
	v_fmac_f32_e32 v5, v73, v41
	v_fmac_f32_e32 v18, v58, v42
	v_fmac_f32_e32 v19, v62, v42
	v_fmac_f32_e32 v20, v66, v42
	v_fmac_f32_e32 v21, v70, v42
	v_fmac_f32_e32 v5, v74, v42
	v_fmac_f32_e32 v18, v59, v43
	v_fmac_f32_e32 v19, v63, v43
	v_fmac_f32_e32 v20, v67, v43
	v_fmac_f32_e32 v21, v71, v43
	v_fmac_f32_e32 v5, v75, v43
	v_add_u32_e32 v7, 16, v7
	s_waitcnt vmcnt(8)
	ds_read_b128 v[56:59], v7
	ds_read_b128 v[60:63], v7 offset:8192
	ds_read_b128 v[64:67], v7 offset:16384
	ds_read_b128 v[68:71], v7 offset:24576
	ds_read_b128 v[72:75], v7 offset:32768
	s_waitcnt lgkmcnt(0)
	v_fmac_f32_e32 v18, v56, v44
	v_fmac_f32_e32 v19, v60, v44
	v_fmac_f32_e32 v20, v64, v44
	v_fmac_f32_e32 v21, v68, v44
	v_fmac_f32_e32 v5, v72, v44
	v_fmac_f32_e32 v18, v57, v45
	v_fmac_f32_e32 v19, v61, v45
	v_fmac_f32_e32 v20, v65, v45
	v_fmac_f32_e32 v21, v69, v45
	v_fmac_f32_e32 v5, v73, v45
	v_fmac_f32_e32 v18, v58, v46
	v_fmac_f32_e32 v19, v62, v46
	v_fmac_f32_e32 v20, v66, v46
	v_fmac_f32_e32 v21, v70, v46
	v_fmac_f32_e32 v5, v74, v46
	v_fmac_f32_e32 v18, v59, v47
	v_fmac_f32_e32 v19, v63, v47
	v_fmac_f32_e32 v20, v67, v47
	v_fmac_f32_e32 v21, v71, v47
	v_fmac_f32_e32 v5, v75, v47
	v_add_u32_e32 v7, 16, v7
	s_waitcnt vmcnt(4)
	ds_read_b128 v[56:59], v7
	ds_read_b128 v[60:63], v7 offset:8192
	ds_read_b128 v[64:67], v7 offset:16384
	ds_read_b128 v[68:71], v7 offset:24576
	ds_read_b128 v[72:75], v7 offset:32768
	s_waitcnt lgkmcnt(0)
	v_fmac_f32_e32 v18, v56, v48
	v_fmac_f32_e32 v19, v60, v48
	v_fmac_f32_e32 v20, v64, v48
	v_fmac_f32_e32 v21, v68, v48
	v_fmac_f32_e32 v5, v72, v48
	v_fmac_f32_e32 v18, v57, v49
	v_fmac_f32_e32 v19, v61, v49
	v_fmac_f32_e32 v20, v65, v49
	v_fmac_f32_e32 v21, v69, v49
	v_fmac_f32_e32 v5, v73, v49
	v_fmac_f32_e32 v18, v58, v50
	v_fmac_f32_e32 v19, v62, v50
	v_fmac_f32_e32 v20, v66, v50
	v_fmac_f32_e32 v21, v70, v50
	v_fmac_f32_e32 v5, v74, v50
	v_fmac_f32_e32 v18, v59, v51
	v_fmac_f32_e32 v19, v63, v51
	v_fmac_f32_e32 v20, v67, v51
	v_fmac_f32_e32 v21, v71, v51
	v_fmac_f32_e32 v5, v75, v51
	v_add_u32_e32 v7, 16, v7
	s_waitcnt vmcnt(0)
	ds_read_b128 v[56:59], v7
	ds_read_b128 v[60:63], v7 offset:8192
	ds_read_b128 v[64:67], v7 offset:16384
	ds_read_b128 v[68:71], v7 offset:24576
	ds_read_b128 v[72:75], v7 offset:32768
	s_waitcnt lgkmcnt(0)
	v_fmac_f32_e32 v18, v56, v52
	v_fmac_f32_e32 v19, v60, v52
	v_fmac_f32_e32 v20, v64, v52
	v_fmac_f32_e32 v21, v68, v52
	v_fmac_f32_e32 v5, v72, v52
	v_fmac_f32_e32 v18, v57, v53
	v_fmac_f32_e32 v19, v61, v53
	v_fmac_f32_e32 v20, v65, v53
	v_fmac_f32_e32 v21, v69, v53
	v_fmac_f32_e32 v5, v73, v53
	v_fmac_f32_e32 v18, v58, v54
	v_fmac_f32_e32 v19, v62, v54
	v_fmac_f32_e32 v20, v66, v54
	v_fmac_f32_e32 v21, v70, v54
	v_fmac_f32_e32 v5, v74, v54
	v_fmac_f32_e32 v18, v59, v55
	v_fmac_f32_e32 v19, v63, v55
	v_fmac_f32_e32 v20, v67, v55
	v_fmac_f32_e32 v21, v71, v55
	v_fmac_f32_e32 v5, v75, v55
	v_add_u32_e32 v7, 16, v7
	ds_write2st64_b32 v12, v18, v19 offset0:160 offset1:161
	ds_write2st64_b32 v12, v20, v21 offset0:162 offset1:163
	ds_write_b32 v12, v5 offset:41984
	s_waitcnt lgkmcnt(0)
	s_barrier
	s_and_saveexec_b64 s[0:1], vcc
	s_cbranch_execz .LBB0_12
	s_mul_i32 s6, s19, 0xffffffa0
	s_add_i32 s6, s6, s18
	s_lshl_b32 s6, s6, 6
	s_add_i32 s7, s6, s20
	v_or_b32_e32 v24, s7, v4
	v_add_u32_e32 v5, v10, v1
	s_mov_b64 s[22:23], s[54:55]
	v_ashrrev_i32_e32 v25, 31, v24
	ds_read2st64_b32 v[16:17], v5 offset0:160 offset1:165
	ds_read2st64_b32 v[18:19], v5 offset0:170 offset1:175
	ds_read2st64_b32 v[20:21], v5 offset0:180 offset1:185
	ds_read2st64_b32 v[22:23], v5 offset0:190 offset1:195
	s_waitcnt lgkmcnt(3)
	v_add_f32_e32 v7, 0, v16
	v_lshl_add_u64 v[24:25], v[24:25], 2, s[22:23]
	global_load_dword v5, v[24:25], off
	v_add_f32_e32 v7, v7, v17
	s_waitcnt lgkmcnt(2)
	v_add_f32_e32 v7, v7, v18
	v_add_f32_e32 v7, v7, v19
	s_waitcnt lgkmcnt(1)
	v_add_f32_e32 v7, v7, v20
	v_mad_u64_u32 v[24:25], s[20:21], s19, 5, v[34:35]
	v_mov_b64_e32 v[26:27], s[4:5]
	v_add_f32_e32 v7, v7, v21
	v_mad_i64_i32 v[24:25], s[20:21], v24, s2, v[26:27]
	s_ashr_i32 s7, s6, 31
	s_waitcnt lgkmcnt(0)
	v_add_f32_e32 v7, v7, v22
	v_lshl_add_u64 v[24:25], s[6:7], 2, v[24:25]
	v_add_f32_e32 v7, v7, v23
	v_lshl_add_u64 v[16:17], v[24:25], 0, v[8:9]
	s_waitcnt vmcnt(0)
	v_add_f32_e32 v5, v7, v5
	global_store_dword v[16:17], v5, off
	s_branch .LBB0_12

.LBB0_227:
	s_or_b64 exec, exec, s[6:7]
	s_lshr_b32 s10, s22, 1
	s_mov_b64 s[6:7], -1
	s_and_b64 vcc, exec, s[4:5]
	s_waitcnt lgkmcnt(0)
	s_barrier
	s_cbranch_vccz .LBB0_331
	s_movk_i32 s41, 0x480
	s_cmp_eq_u32 s22, 3
	s_cselect_b32 s41, 0x400, s41
	s_mov_b32 s53, 0x3e0293ee
	v_readlane_b32 s24, v253, 8
	v_readlane_b32 s25, v253, 9
	s_mul_i32 s1, s10, 0xe880
	s_add_u32 s24, s24, s1
	s_addc_u32 s25, s25, 0
	s_add_u32 s26, s92, 0x18e00000
	s_addc_u32 s27, s93, 0
	s_add_u32 s28, s92, 0x2ae00000
	s_addc_u32 s29, s93, 0
	v_readfirstlane_b32 s36, v172
	s_lshr_b32 s36, s36, 6
	s_and_b32 s37, s36, 3
	s_lshr_b32 s38, s36, 2
	s_lshl_b32 s39, s37, 3
	s_cmp_gt_u32 s37, 1
	s_cselect_b32 s1, 8, 0
	s_add_u32 s39, s39, s1
	v_and_b32_e32 v192, 15, v246
	v_lshrrev_b32_e32 v193, 4, v246
	v_lshrrev_b32_e32 v224, 4, v172
	v_and_b32_e32 v225, 15, v172
	v_lshlrev_b32_e32 v194, 15, v224
	v_lshl_add_u32 v194, v225, 4, v194
	v_add_u32_e32 v195, 0x100000, v194
	v_mul_u32_u24_e32 v196, 0x120, v224
	v_lshl_add_u32 v196, v225, 4, v196
	v_mul_u32_u24_e32 v197, 0x120, v224
	v_lshl_add_u32 v197, v225, 4, v197
	v_add_u32_e32 v197, 0x4800, v197
	v_mul_u32_u24_e32 v199, 0x120, v192
	v_lshl_add_u32 v199, v193, 4, v199
	s_mul_i32 s1, s39, 0x120
	v_add_u32_e32 v198, s1, v199
	v_lshrrev_b32_e32 v224, 2, v192
	v_lshl_add_u32 v224, v193, 2, v224
	v_mul_u32_u24_e32 v201, 0x120, v224
	v_and_b32_e32 v225, 3, v192
	v_lshl_add_u32 v201, v225, 3, v201
	v_add_u32_e32 v201, 0x4800, v201
	s_mul_i32 s1, s39, 0x120
	v_add_u32_e32 v200, s1, v201
	v_lshl_add_u32 v228, s37, 4, v192
	v_add_u32_e32 v224, -8, v228
	v_max_i32_e32 v224, 0, v224
	v_min_i32_e32 v229, 48, v224
	v_lshl_add_u32 v230, v193, 2, s39
	v_add_u32_e32 v224, 0, v230
	v_sub_u32_e32 v225, v224, v229
	v_cmp_gt_u32_e32 vcc, 16, v225
	v_sub_u32_e32 v224, v224, v228
	v_add_u32_e32 v224, 15, v224
	v_cndmask_b32_e32 v224, 31, v224, vcc
	v_lshlrev_b32_e32 v202, 2, v224
	v_add_u32_e32 v224, 1, v230
	v_sub_u32_e32 v225, v224, v229
	v_cmp_gt_u32_e32 vcc, 16, v225
	v_sub_u32_e32 v224, v224, v228
	v_add_u32_e32 v224, 15, v224
	v_cndmask_b32_e32 v224, 31, v224, vcc
	v_lshlrev_b32_e32 v203, 2, v224
	v_add_u32_e32 v224, 2, v230
	v_sub_u32_e32 v225, v224, v229
	v_cmp_gt_u32_e32 vcc, 16, v225
	v_sub_u32_e32 v224, v224, v228
	v_add_u32_e32 v224, 15, v224
	v_cndmask_b32_e32 v224, 31, v224, vcc
	v_lshlrev_b32_e32 v204, 2, v224
	v_add_u32_e32 v224, 3, v230
	v_sub_u32_e32 v225, v224, v229
	v_cmp_gt_u32_e32 vcc, 16, v225
	v_sub_u32_e32 v224, v224, v228
	v_add_u32_e32 v224, 15, v224
	v_cndmask_b32_e32 v224, 31, v224, vcc
	v_lshlrev_b32_e32 v205, 2, v224
	v_add_u32_e32 v224, 16, v230
	v_sub_u32_e32 v225, v224, v229
	v_cmp_gt_u32_e32 vcc, 16, v225
	v_sub_u32_e32 v224, v224, v228
	v_add_u32_e32 v224, 15, v224
	v_cndmask_b32_e32 v224, 31, v224, vcc
	v_lshlrev_b32_e32 v206, 2, v224
	v_add_u32_e32 v224, 17, v230
	v_sub_u32_e32 v225, v224, v229
	v_cmp_gt_u32_e32 vcc, 16, v225
	v_sub_u32_e32 v224, v224, v228
	v_add_u32_e32 v224, 15, v224
	v_cndmask_b32_e32 v224, 31, v224, vcc
	v_lshlrev_b32_e32 v207, 2, v224
	v_add_u32_e32 v224, 18, v230
	v_sub_u32_e32 v225, v224, v229
	v_cmp_gt_u32_e32 vcc, 16, v225
	v_sub_u32_e32 v224, v224, v228
	v_add_u32_e32 v224, 15, v224
	v_cndmask_b32_e32 v224, 31, v224, vcc
	v_lshlrev_b32_e32 v208, 2, v224
	v_add_u32_e32 v224, 19, v230
	v_sub_u32_e32 v225, v224, v229
	v_cmp_gt_u32_e32 vcc, 16, v225
	v_sub_u32_e32 v224, v224, v228
	v_add_u32_e32 v224, 15, v224
	v_cndmask_b32_e32 v224, 31, v224, vcc
	v_lshlrev_b32_e32 v209, 2, v224
	v_lshlrev_b32_e32 v210, 15, v192
	v_lshl_add_u32 v210, v193, 4, v210
	v_lshlrev_b32_e32 v211, 15, v192
	v_lshl_add_u32 v211, v193, 3, v211
	v_and_b32_e32 v224, 1, v193
	v_mul_u32_u24_e32 v224, 24, v224
	v_add_u32_e32 v211, v211, v224
	v_lshlrev_b32_e32 v212, 13, v192
	v_lshl_add_u32 v212, v193, 3, v212
	v_add_u32_e32 v212, v212, v224
	v_lshrrev_b32_e32 v224, 5, v172
	v_and_b32_e32 v225, 31, v172
	v_cmp_gt_u32_e32 vcc, 15, v224
	v_cmp_gt_u32_e64 s[22:23], 31, v225
	s_and_b64 s[22:23], s[22:23], vcc
	v_mul_u32_u24_e32 v224, 31, v224
	v_add_lshl_u32 v224, v224, v225, 2
	v_cndmask_b32_e64 v213, 0, v224, s[22:23]
	v_lshlrev_b32_e32 v214, 2, v172
	v_add_u32_e32 v214, 0x12000, v214
	v_xor_b32_e32 v215, 16, v246
	v_lshlrev_b32_e32 v215, 2, v215
	v_xor_b32_e32 v216, 32, v246
	v_lshlrev_b32_e32 v216, 2, v216
	v_xor_b32_e32 v217, 48, v246
	v_lshlrev_b32_e32 v217, 2, v217
	s_mov_b32 s40, s62
	s_cmp_ge_u32 s40, 0x400
	s_cbranch_scc1 .Lna_dec_ctx_0
	s_mov_b32 s45, 0
	s_cmp_eq_u32 s94, 0x100
	s_cbranch_scc0 .Lna_dec_gen_0
	s_lshr_b32 s1, s40, 8
	s_and_b32 s2, s40, 0xff
	s_lshl_b32 s1, s1, 5
	s_and_b32 s4, s2, 7
	s_lshl_b32 s4, s4, 2
	s_add_u32 s1, s1, s4
	s_lshr_b32 s4, s2, 6
	s_add_u32 s1, s1, s4
	s_bfe_u32 s44, s2, 0x30003
	s_branch .Lna_dec_l2_0

.Lna_tb_done0:
	s_lshl_b32 s1, s1, 15
	s_lshl_b32 s2, s43, 8
	s_add_u32 s1, s1, s2
	s_add_u32 s1, s1, 0x2000
	s_add_u32 s54, s26, s1
	s_addc_u32 s55, s27, 0
	s_add_u32 s56, s54, 0x2000
	s_addc_u32 s57, s55, 0
	global_load_dwordx4 v[96:99], v194, s[54:55]
	global_load_dwordx4 v[100:103], v194, s[56:57]
	global_load_dwordx4 v[104:107], v195, s[54:55]
	global_load_dwordx4 v[108:111], v195, s[56:57]
	v_mov_b64_e32 v[0:1], 0
	v_mov_b64_e32 v[2:3], 0
	v_mov_b64_e32 v[4:5], 0
	v_mov_b64_e32 v[6:7], 0
	v_mov_b64_e32 v[8:9], 0
	v_mov_b64_e32 v[10:11], 0
	v_mov_b64_e32 v[12:13], 0
	v_mov_b64_e32 v[14:15], 0
	v_mov_b64_e32 v[16:17], 0
	v_mov_b64_e32 v[18:19], 0
	v_mov_b64_e32 v[20:21], 0
	v_mov_b64_e32 v[22:23], 0
	v_mov_b64_e32 v[24:25], 0
	v_mov_b64_e32 v[26:27], 0
	v_mov_b64_e32 v[28:29], 0
	v_mov_b64_e32 v[30:31], 0
	v_mov_b64_e32 v[32:33], 0
	v_mov_b64_e32 v[34:35], 0
	v_mov_b64_e32 v[36:37], 0
	v_mov_b64_e32 v[38:39], 0
	v_mov_b64_e32 v[40:41], 0
	v_mov_b64_e32 v[42:43], 0
	v_mov_b64_e32 v[44:45], 0
	v_mov_b64_e32 v[46:47], 0
	v_mov_b64_e32 v[48:49], 0
	v_mov_b64_e32 v[50:51], 0
	v_mov_b64_e32 v[52:53], 0
	v_mov_b64_e32 v[54:55], 0
	v_mov_b64_e32 v[56:57], 0
	v_mov_b64_e32 v[58:59], 0
	v_mov_b64_e32 v[60:61], 0
	v_mov_b64_e32 v[62:63], 0
	v_mov_b32_e32 v218, 0xf149f2ca
	v_mov_b32_e32 v221, 0xf149f2ca
	v_mov_b32_e32 v219, 0xf149f2ca
	v_mov_b32_e32 v222, 0xf149f2ca
	v_mov_b32_e32 v220, 0
	v_mov_b32_e32 v223, 0
	s_waitcnt vmcnt(4)
	v_mul_f32_e32 v236, 0x3fb8aa3b, v236
	v_cndmask_b32_e64 v236, v247, v236, s[22:23]
	ds_write_b32 v214, v236
	s_waitcnt vmcnt(0)
	v_mov_b32_e32 v234, v196
	v_mov_b32_e32 v235, v197
	ds_write_b128 v234, v[96:99]
	ds_write_b128 v235, v[100:103]
	ds_write_b128 v234, v[104:107] offset:9216
	ds_write_b128 v235, v[108:111] offset:9216
	s_waitcnt lgkmcnt(0)
	s_barrier
	s_branch .Lna_itloop
.Lna_unit_next:
	v_mov_b64_e32 v[0:1], 0
	v_mov_b64_e32 v[2:3], 0
	v_mov_b64_e32 v[4:5], 0
	v_mov_b64_e32 v[6:7], 0
	v_mov_b64_e32 v[8:9], 0
	v_mov_b64_e32 v[10:11], 0
	v_mov_b64_e32 v[12:13], 0
	v_mov_b64_e32 v[14:15], 0
	v_mov_b64_e32 v[16:17], 0
	v_mov_b64_e32 v[18:19], 0
	v_mov_b64_e32 v[20:21], 0
	v_mov_b64_e32 v[22:23], 0
	v_mov_b64_e32 v[24:25], 0
	v_mov_b64_e32 v[26:27], 0
	v_mov_b64_e32 v[28:29], 0
	v_mov_b64_e32 v[30:31], 0
	v_mov_b64_e32 v[32:33], 0
	v_mov_b64_e32 v[34:35], 0
	v_mov_b64_e32 v[36:37], 0
	v_mov_b64_e32 v[38:39], 0
	v_mov_b64_e32 v[40:41], 0
	v_mov_b64_e32 v[42:43], 0
	v_mov_b64_e32 v[44:45], 0
	v_mov_b64_e32 v[46:47], 0
	v_mov_b64_e32 v[48:49], 0
	v_mov_b64_e32 v[50:51], 0
	v_mov_b64_e32 v[52:53], 0
	v_mov_b64_e32 v[54:55], 0
	v_mov_b64_e32 v[56:57], 0
	v_mov_b64_e32 v[58:59], 0
	v_mov_b64_e32 v[60:61], 0
	v_mov_b64_e32 v[62:63], 0
	v_mov_b32_e32 v218, 0xf149f2ca
	v_mov_b32_e32 v221, 0xf149f2ca
	v_mov_b32_e32 v219, 0xf149f2ca
	v_mov_b32_e32 v222, 0xf149f2ca
	v_mov_b32_e32 v220, 0
	v_mov_b32_e32 v223, 0
	s_waitcnt vmcnt(12)
	v_mul_f32_e32 v236, 0x3fb8aa3b, v236
	v_cndmask_b32_e64 v236, v247, v236, s[22:23]
	ds_write_b32 v214, v236
	s_waitcnt vmcnt(8)
	v_mov_b32_e32 v234, v196
	v_mov_b32_e32 v235, v197
	ds_write_b128 v234, v[96:99]
	ds_write_b128 v235, v[100:103]
	ds_write_b128 v234, v[104:107] offset:9216
	ds_write_b128 v235, v[108:111] offset:9216
	s_waitcnt lgkmcnt(0)
	s_barrier

.Lna_noload:
	s_cmp_lt_u32 s52, s50
	s_cbranch_scc0 .Lna_ctx
	s_add_u32 s1, s49, s52
	s_sub_u32 s2, s1, s47
	s_cmp_lt_u32 s2, 8
	s_cselect_b32 s4, 1, 0
	s_sub_u32 s2, s1, s48
	s_cmp_lt_u32 s2, 8
	s_cselect_b32 s5, 1, 0
	s_or_b32 s6, s4, s5
	s_cmp_eq_u32 s6, 0
	s_cbranch_scc1 .Lna_endcompute
	s_sub_u32 s2, s1, s46
	s_add_u32 s2, s2, 7
	s_cmp_eq_u32 s4, 1
	s_cselect_b32 s6, s2, 15
	s_lshl_b32 s6, s6, 7
	s_add_u32 s78, s6, 0x12000
	s_sub_u32 s2, s2, 1
	s_cmp_eq_u32 s5, 1
	s_cselect_b32 s6, s2, 15
	s_lshl_b32 s6, s6, 7
	s_add_u32 s79, s6, 0x12000
	v_add_u32_e32 v232, s66, v198
	v_add_u32_e32 v233, s66, v200
	ds_read_b128 v[112:115], v232 offset:0
	ds_read_b128 v[116:119], v232 offset:4608
	ds_read_b128 v[120:123], v232 offset:64
	ds_read_b128 v[124:127], v232 offset:4672
	ds_read_b128 v[128:131], v232 offset:128
	ds_read_b128 v[132:135], v232 offset:4736
	ds_read_b128 v[136:139], v232 offset:192
	ds_read_b128 v[140:143], v232 offset:4800
	s_waitcnt lgkmcnt(6)
	v_mfma_f32_16x16x32_bf16 v[144:147], v[112:115], v[64:67], 0
	v_mfma_f32_16x16x32_bf16 v[148:151], v[116:119], v[64:67], 0
	v_add_u32_e32 v160, s78, v202
	ds_read_b32 v160, v160
	v_add_u32_e32 v161, s78, v203
	ds_read_b32 v161, v161
	v_add_u32_e32 v162, s78, v204
	ds_read_b32 v162, v162
	v_add_u32_e32 v163, s78, v205
	ds_read_b32 v163, v163
	v_add_u32_e32 v164, s78, v206
	ds_read_b32 v164, v164
	v_add_u32_e32 v165, s78, v207
	ds_read_b32 v165, v165
	v_add_u32_e32 v166, s78, v208
	ds_read_b32 v166, v166
	v_add_u32_e32 v167, s78, v209
	ds_read_b32 v167, v167
	s_waitcnt lgkmcnt(12)
	v_mfma_f32_16x16x32_bf16 v[144:147], v[120:123], v[68:71], v[144:147]
	v_mfma_f32_16x16x32_bf16 v[148:151], v[124:127], v[68:71], v[148:151]
	s_waitcnt lgkmcnt(10)
	v_mfma_f32_16x16x32_bf16 v[144:147], v[128:131], v[72:75], v[144:147]
	v_mfma_f32_16x16x32_bf16 v[148:151], v[132:135], v[72:75], v[148:151]
	s_waitcnt lgkmcnt(8)
	v_mfma_f32_16x16x32_bf16 v[144:147], v[136:139], v[76:79], v[144:147]
	v_mfma_f32_16x16x32_bf16 v[148:151], v[140:143], v[76:79], v[148:151]
	s_waitcnt lgkmcnt(0)
	v_add_u32_e32 v179, s79, v202
	ds_read_b32 v179, v179
	v_add_u32_e32 v180, s79, v203
	ds_read_b32 v180, v180
	v_add_u32_e32 v181, s79, v204
	ds_read_b32 v181, v181
	v_add_u32_e32 v182, s79, v205
	ds_read_b32 v182, v182
	v_add_u32_e32 v183, s79, v206
	ds_read_b32 v183, v183
	v_add_u32_e32 v184, s79, v207
	ds_read_b32 v184, v184
	v_add_u32_e32 v185, s79, v208
	ds_read_b32 v185, v185
	v_add_u32_e32 v186, s79, v209
	ds_read_b32 v186, v186
	v_mfma_f32_16x16x32_bf16 v[152:155], v[112:115], v[80:83], 0
	v_mfma_f32_16x16x32_bf16 v[156:159], v[116:119], v[80:83], 0
	ds_read_b64_tr_b16 v[112:113], v233 offset:0
	ds_read_b64_tr_b16 v[114:115], v233 offset:4608
	ds_read_b64_tr_b16 v[116:117], v233 offset:32
	ds_read_b64_tr_b16 v[118:119], v233 offset:4640
	v_fma_f32 v160, v144, s53, v160
	v_fma_f32 v161, v145, s53, v161
	v_fma_f32 v162, v146, s53, v162
	v_fma_f32 v163, v147, s53, v163
	v_fma_f32 v164, v148, s53, v164
	v_fma_f32 v165, v149, s53, v165
	v_fma_f32 v166, v150, s53, v166
	v_fma_f32 v167, v151, s53, v167
	v_max3_f32 v224, v160, v161, v162
	v_max3_f32 v224, v224, v163, v164
	v_mfma_f32_16x16x32_bf16 v[152:155], v[120:123], v[84:87], v[152:155]
	v_mfma_f32_16x16x32_bf16 v[156:159], v[124:127], v[84:87], v[156:159]
	s_waitcnt lgkmcnt(4)
	ds_read_b64_tr_b16 v[120:121], v233 offset:64
	ds_read_b64_tr_b16 v[122:123], v233 offset:4672
	ds_read_b64_tr_b16 v[124:125], v233 offset:96
	ds_read_b64_tr_b16 v[126:127], v233 offset:4704
	v_max3_f32 v224, v224, v165, v166
	v_max_f32_e32 v224, v224, v167
	v_cmp_gt_f32_e32 vcc, v224, v219
	s_cbranch_vccnz .Lna_rare_L_b0

.Lna_ctx_grp:
	ds_read_b128 v[112:115], v232 offset:0
	ds_read_b128 v[116:119], v232 offset:4608
	ds_read_b128 v[120:123], v232 offset:64
	ds_read_b128 v[124:127], v232 offset:4672
	ds_read_b128 v[128:131], v232 offset:128
	ds_read_b128 v[132:135], v232 offset:4736
	ds_read_b128 v[136:139], v232 offset:192
	ds_read_b128 v[140:143], v232 offset:4800
	s_waitcnt lgkmcnt(6)
	v_mfma_f32_16x16x32_bf16 v[144:147], v[112:115], v[64:67], 0
	v_mfma_f32_16x16x32_bf16 v[148:151], v[116:119], v[64:67], 0
	s_waitcnt lgkmcnt(4)
	v_mfma_f32_16x16x32_bf16 v[144:147], v[120:123], v[68:71], v[144:147]
	v_mfma_f32_16x16x32_bf16 v[148:151], v[124:127], v[68:71], v[148:151]
	s_waitcnt lgkmcnt(2)
	v_mfma_f32_16x16x32_bf16 v[144:147], v[128:131], v[72:75], v[144:147]
	v_mfma_f32_16x16x32_bf16 v[148:151], v[132:135], v[72:75], v[148:151]
	s_waitcnt lgkmcnt(0)
	v_mfma_f32_16x16x32_bf16 v[144:147], v[136:139], v[76:79], v[144:147]
	v_mfma_f32_16x16x32_bf16 v[148:151], v[140:143], v[76:79], v[148:151]
	v_mfma_f32_16x16x32_bf16 v[152:155], v[112:115], v[80:83], 0
	v_mfma_f32_16x16x32_bf16 v[156:159], v[116:119], v[80:83], 0
	ds_read_b64_tr_b16 v[112:113], v233 offset:0
	ds_read_b64_tr_b16 v[114:115], v233 offset:4608
	ds_read_b64_tr_b16 v[116:117], v233 offset:32
	ds_read_b64_tr_b16 v[118:119], v233 offset:4640
	s_nop 0
	v_fma_f32 v160, v144, s53, -v218
	v_fma_f32 v161, v145, s53, -v218
	v_fma_f32 v162, v146, s53, -v218
	v_fma_f32 v163, v147, s53, -v218
	v_fma_f32 v164, v148, s53, -v218
	v_fma_f32 v165, v149, s53, -v218
	v_fma_f32 v166, v150, s53, -v218
	v_fma_f32 v167, v151, s53, -v218
	v_mfma_f32_16x16x32_bf16 v[152:155], v[120:123], v[84:87], v[152:155]
	v_mfma_f32_16x16x32_bf16 v[156:159], v[124:127], v[84:87], v[156:159]
	ds_read_b64_tr_b16 v[120:121], v233 offset:64
	ds_read_b64_tr_b16 v[122:123], v233 offset:4672
	ds_read_b64_tr_b16 v[124:125], v233 offset:96
	ds_read_b64_tr_b16 v[126:127], v233 offset:4704
	v_max3_f32 v224, v160, v161, v162
	v_max3_f32 v224, v224, v163, v164
	v_max3_f32 v224, v224, v165, v166
	v_max_f32_e32 v224, v224, v167
	v_cmp_lt_f32_e32 vcc, 0x41000000, v224
	s_cbranch_vccnz .Lna_rare_C_b0

.Lna_cont_C_b1:
	v_exp_f32_e32 v179, v179
	v_exp_f32_e32 v180, v180
	v_exp_f32_e32 v181, v181
	s_waitcnt lgkmcnt(6)
	v_mfma_f32_16x16x32_bf16 v[16:19], v[128:131], v[168:171], v[16:19]
	v_exp_f32_e32 v182, v182
	v_exp_f32_e32 v183, v183
	v_exp_f32_e32 v184, v184
	v_exp_f32_e32 v185, v185
	s_waitcnt lgkmcnt(4)
	v_mfma_f32_16x16x32_bf16 v[20:23], v[132:135], v[168:171], v[20:23]
	v_exp_f32_e32 v186, v186
	v_add_f32_e32 v228, v179, v180
	v_add_f32_e32 v229, v181, v182
	v_add_f32_e32 v230, v183, v184
	s_waitcnt lgkmcnt(2)
	v_mfma_f32_16x16x32_bf16 v[24:27], v[136:139], v[168:171], v[24:27]
	v_add_f32_e32 v231, v185, v186
	v_add_f32_e32 v228, v228, v229
	v_add_f32_e32 v230, v230, v231
	v_add_f32_e32 v228, v228, v230
	s_waitcnt lgkmcnt(0)
	v_mfma_f32_16x16x32_bf16 v[28:31], v[140:143], v[168:171], v[28:31]
	v_add_f32_e32 v223, v223, v228
	v_cvt_pk_bf16_f32 v188, v179, v180
	v_cvt_pk_bf16_f32 v189, v181, v182
	v_cvt_pk_bf16_f32 v190, v183, v184
	v_cvt_pk_bf16_f32 v191, v185, v186
	s_nop 1
	v_mfma_f32_16x16x32_bf16 v[32:35], v[112:115], v[188:191], v[32:35]
	v_mfma_f32_16x16x32_bf16 v[36:39], v[116:119], v[188:191], v[36:39]
	v_mfma_f32_16x16x32_bf16 v[40:43], v[120:123], v[188:191], v[40:43]
	v_mfma_f32_16x16x32_bf16 v[44:47], v[124:127], v[188:191], v[44:47]
	v_mfma_f32_16x16x32_bf16 v[48:51], v[128:131], v[188:191], v[48:51]
	v_mfma_f32_16x16x32_bf16 v[52:55], v[132:135], v[188:191], v[52:55]
	v_mfma_f32_16x16x32_bf16 v[56:59], v[136:139], v[188:191], v[56:59]
	v_mfma_f32_16x16x32_bf16 v[60:63], v[140:143], v[188:191], v[60:63]
	v_add_u32_e32 v232, 0x2400, v232
	v_add_u32_e32 v233, 0x2400, v233
	s_add_u32 s90, s90, 1
	s_cmp_lt_u32 s90, 2
	s_cbranch_scc1 .Lna_ctx_grp
.Lna_endcompute:
	s_cmp_eq_u32 s67, 0
	s_cbranch_scc1 .Lna_nostore
	s_sub_u32 s1, 0x9000, s66
	v_add_u32_e32 v234, s1, v196
	v_add_u32_e32 v235, s1, v197
	s_waitcnt vmcnt(0)
	ds_write_b128 v234, v[96:99]
	ds_write_b128 v235, v[100:103]
	ds_write_b128 v234, v[104:107] offset:9216
	ds_write_b128 v235, v[108:111] offset:9216
.Lna_nostore:
	s_waitcnt lgkmcnt(0)
	s_barrier
	s_sub_u32 s66, 0x9000, s66
	s_add_u32 s52, s52, 1
	s_cmp_lt_u32 s52, s51
	s_cbranch_scc1 .Lna_it
	s_lshl_b32 s6, s43, 8
	s_lshl_b32 s7, s8, 15
	s_add_u32 s7, s7, s6
	s_add_u32 s7, s7, 0x6000
	s_add_u32 s72, s26, s7
	s_addc_u32 s73, s27, 0
	s_lshl_b32 s7, s8, 13
	s_add_u32 s7, s7, s6
	s_add_u32 s12, s28, s7
	s_addc_u32 s13, s29, 0
	global_load_dwordx4 v[112:115], v211, s[72:73] offset:0
	global_load_dwordx4 v[116:119], v211, s[72:73] offset:64
	global_load_dwordx4 v[120:123], v211, s[72:73] offset:128
	global_load_dwordx4 v[124:127], v211, s[72:73] offset:192
	s_lshl_b32 s7, s9, 15
	s_add_u32 s7, s7, s6
	s_add_u32 s7, s7, 0x6000
	s_add_u32 s16, s26, s7
	s_addc_u32 s17, s27, 0
	s_lshl_b32 s7, s9, 13
	s_add_u32 s7, s7, s6
	s_add_u32 s30, s28, s7
	s_addc_u32 s31, s29, 0
	global_load_dwordx4 v[128:131], v211, s[16:17] offset:0
	global_load_dwordx4 v[132:135], v211, s[16:17] offset:64
	global_load_dwordx4 v[136:139], v211, s[16:17] offset:128
	global_load_dwordx4 v[140:143], v211, s[16:17] offset:192
	s_add_u32 s15, s40, s94
	s_cmp_lt_u32 s15, s41
	s_cselect_b32 s40, s15, s40
	s_cmp_ge_u32 s40, 0x400
	s_cbranch_scc1 .Lna_dec_ctx_1
	s_mov_b32 s45, 0
	s_cmp_eq_u32 s94, 0x100
	s_cbranch_scc0 .Lna_dec_gen_1
	s_lshr_b32 s1, s40, 8
	s_and_b32 s2, s40, 0xff
	s_lshl_b32 s1, s1, 5
	s_and_b32 s4, s2, 7
	s_lshl_b32 s4, s4, 2
	s_add_u32 s1, s1, s4
	s_lshr_b32 s4, s2, 6
	s_add_u32 s1, s1, s4
	s_bfe_u32 s44, s2, 0x30003
	s_branch .Lna_dec_l2_1
